# fused GEMM+LayerNorm: residual tile stores write through at agent scope (sc1) from a pipelined epilogue; no whole-L2 write-back for prompt tiles (kept for the K-split sample tiles)
# speedup vs baseline: 1.0234x; 1.0129x over previous
.LBB0_48:
	s_or_b64 exec, exec, s[22:23]
	v_mov_b32_e32 v0, v211
	s_and_b64 vcc, exec, s[16:17]
	v_ashrrev_i32_e32 v130, 2, v0
	v_and_b32_e32 v130, 0xffffffc0, v130
	v_and_or_b32 v131, v0, 15, s20
	v_add_u32_e32 v142, v131, v130
	v_lshrrev_b32_e32 v130, 1, v0
	v_lshrrev_b32_e32 v131, 2, v0
	v_and_b32_e32 v130, 0x60, v130
	v_and_b32_e32 v131, 12, v131
	v_or3_b32 v148, v130, v131, s18
	v_or_b32_e32 v138, 48, v142
	v_or_b32_e32 v144, 16, v142
	v_or_b32_e32 v140, 32, v142
	v_add_u32_e32 v136, 0x80, v142
	v_add_u32_e32 v130, 0xb0, v142
	v_add_u32_e32 v134, 0x90, v142
	v_add_u32_e32 v132, 0xa0, v142
	v_ashrrev_i32_e32 v149, 31, v148
	s_mov_b64 s[18:19], -1
	v_ashrrev_i32_e32 v143, 31, v142
	v_ashrrev_i32_e32 v139, 31, v138
	v_ashrrev_i32_e32 v145, 31, v144
	v_ashrrev_i32_e32 v141, 31, v140
	v_ashrrev_i32_e32 v131, 31, v130
	v_ashrrev_i32_e32 v137, 31, v136
	v_ashrrev_i32_e32 v135, 31, v134
	v_ashrrev_i32_e32 v133, 31, v132
	s_cbranch_vccz .LBB0_50
	v_lshlrev_b64 v[204:205], 10, v[142:143]
	v_lshl_add_u64 v[204:205], v[204:205], 0, v[148:149]
	v_lshlrev_b64 v[204:205], 2, v[204:205]
	v_lshl_add_u64 v[206:207], s[10:11], 0, v[204:205]
	s_mov_b32 s16, 0x3fb504f3
	v_lshl_add_u64 v[204:205], s[8:9], 0, v[204:205]
	v_lshlrev_b64 v[208:209], 10, v[144:145]
	v_lshl_add_u64 v[208:209], v[208:209], 0, v[148:149]
	v_lshlrev_b64 v[208:209], 2, v[208:209]
	v_lshl_add_u64 v[222:223], s[10:11], 0, v[208:209]
	v_lshl_add_u64 v[208:209], s[8:9], 0, v[208:209]
	v_lshlrev_b64 v[226:227], 10, v[140:141]
	v_lshl_add_u64 v[226:227], v[226:227], 0, v[148:149]
	v_lshlrev_b64 v[226:227], 2, v[226:227]
	v_lshl_add_u64 v[228:229], s[10:11], 0, v[226:227]
	v_lshl_add_u64 v[226:227], s[8:9], 0, v[226:227]
	v_lshlrev_b64 v[230:231], 10, v[138:139]
	v_lshl_add_u64 v[230:231], v[230:231], 0, v[148:149]
	v_lshlrev_b64 v[230:231], 2, v[230:231]
	v_lshl_add_u64 v[232:233], s[10:11], 0, v[230:231]
	v_lshl_add_u64 v[230:231], s[8:9], 0, v[230:231]
	s_mov_b64 s[18:19], 0
	v_lshlrev_b64 v[234:235], 10, v[136:137]
	v_lshl_add_u64 v[234:235], v[234:235], 0, v[148:149]
	v_lshlrev_b64 v[234:235], 2, v[234:235]
	v_lshl_add_u64 v[236:237], s[10:11], 0, v[234:235]
	v_lshl_add_u64 v[234:235], s[8:9], 0, v[234:235]
	v_lshlrev_b64 v[238:239], 10, v[134:135]
	v_lshl_add_u64 v[238:239], v[238:239], 0, v[148:149]
	v_lshlrev_b64 v[238:239], 2, v[238:239]
	v_lshl_add_u64 v[240:241], s[10:11], 0, v[238:239]
	v_lshl_add_u64 v[238:239], s[8:9], 0, v[238:239]
	v_lshlrev_b64 v[242:243], 10, v[132:133]
	v_lshl_add_u64 v[242:243], v[242:243], 0, v[148:149]
	v_lshlrev_b64 v[242:243], 2, v[242:243]
	v_lshl_add_u64 v[244:245], s[10:11], 0, v[242:243]
	v_lshl_add_u64 v[242:243], s[8:9], 0, v[242:243]
	v_lshlrev_b64 v[246:247], 10, v[130:131]
	v_lshl_add_u64 v[246:247], v[246:247], 0, v[148:149]
	v_lshlrev_b64 v[246:247], 2, v[246:247]
	v_lshl_add_u64 v[248:249], s[10:11], 0, v[246:247]
	v_lshl_add_u64 v[246:247], s[8:9], 0, v[246:247]
	global_load_dwordx4 v[168:171], v[206:207], off
	global_load_dwordx4 v[172:175], v[206:207], off offset:64
	global_load_dwordx4 v[176:179], v[222:223], off
	global_load_dwordx4 v[180:183], v[222:223], off offset:64
	global_load_dwordx4 v[184:187], v[228:229], off
	global_load_dwordx4 v[188:191], v[228:229], off offset:64
	global_load_dwordx4 v[192:195], v[232:233], off
	global_load_dwordx4 v[196:199], v[232:233], off offset:64
	global_load_dwordx4 v[200:203], v[206:207], off offset:512
	s_waitcnt vmcnt(8)
	v_pk_fma_f32 v[168:169], v[168:169], s[16:17], v[126:127] op_sel_hi:[1,0,1]
	v_pk_fma_f32 v[170:171], v[170:171], s[16:17], v[128:129] op_sel_hi:[1,0,1]
	global_store_dwordx4 v[204:205], v[168:171], off sc1
	s_nop 0
	global_load_dwordx4 v[168:171], v[206:207], off offset:576
	s_waitcnt vmcnt(9)
	v_pk_fma_f32 v[172:173], v[172:173], s[16:17], v[122:123] op_sel_hi:[1,0,1]
	v_pk_fma_f32 v[174:175], v[174:175], s[16:17], v[124:125] op_sel_hi:[1,0,1]
	global_store_dwordx4 v[204:205], v[172:175], off offset:64 sc1
	s_nop 0
	global_load_dwordx4 v[172:175], v[222:223], off offset:512
	s_waitcnt vmcnt(10)
	v_pk_fma_f32 v[178:179], v[178:179], s[16:17], v[120:121] op_sel_hi:[1,0,1]
	v_pk_fma_f32 v[176:177], v[176:177], s[16:17], v[118:119] op_sel_hi:[1,0,1]
	global_store_dwordx4 v[208:209], v[176:179], off sc1
	s_nop 0
	global_load_dwordx4 v[176:179], v[222:223], off offset:576
	s_waitcnt vmcnt(11)
	v_pk_fma_f32 v[182:183], v[182:183], s[16:17], v[116:117] op_sel_hi:[1,0,1]
	v_pk_fma_f32 v[180:181], v[180:181], s[16:17], v[114:115] op_sel_hi:[1,0,1]
	global_store_dwordx4 v[208:209], v[180:183], off offset:64 sc1
	s_nop 0
	global_load_dwordx4 v[180:183], v[228:229], off offset:512
	s_waitcnt vmcnt(12)
	v_pk_fma_f32 v[186:187], v[186:187], s[16:17], v[112:113] op_sel_hi:[1,0,1]
	v_pk_fma_f32 v[184:185], v[184:185], s[16:17], v[110:111] op_sel_hi:[1,0,1]
	global_store_dwordx4 v[226:227], v[184:187], off sc1
	s_nop 0
	global_load_dwordx4 v[184:187], v[228:229], off offset:576
	s_waitcnt vmcnt(13)
	v_pk_fma_f32 v[190:191], v[190:191], s[16:17], v[108:109] op_sel_hi:[1,0,1]
	v_pk_fma_f32 v[188:189], v[188:189], s[16:17], v[106:107] op_sel_hi:[1,0,1]
	global_store_dwordx4 v[226:227], v[188:191], off offset:64 sc1
	s_nop 0
	global_load_dwordx4 v[188:191], v[232:233], off offset:512
	s_waitcnt vmcnt(14)
	v_pk_fma_f32 v[194:195], v[194:195], s[16:17], v[88:89] op_sel_hi:[1,0,1]
	v_pk_fma_f32 v[192:193], v[192:193], s[16:17], v[86:87] op_sel_hi:[1,0,1]
	global_store_dwordx4 v[230:231], v[192:195], off sc1
	s_nop 0
	global_load_dwordx4 v[192:195], v[232:233], off offset:576
	s_waitcnt vmcnt(15)
	v_pk_fma_f32 v[198:199], v[198:199], s[16:17], v[76:77] op_sel_hi:[1,0,1]
	v_pk_fma_f32 v[196:197], v[196:197], s[16:17], v[74:75] op_sel_hi:[1,0,1]
	global_store_dwordx4 v[230:231], v[196:199], off offset:64 sc1
	s_nop 0
	global_load_dwordx4 v[196:199], v[236:237], off
	s_waitcnt vmcnt(16)
	v_pk_fma_f32 v[200:201], v[200:201], s[16:17], v[102:103] op_sel_hi:[1,0,1]
	v_pk_fma_f32 v[202:203], v[202:203], s[16:17], v[104:105] op_sel_hi:[1,0,1]
	global_store_dwordx4 v[204:205], v[200:203], off offset:512 sc1
	s_nop 0
	global_load_dwordx4 v[200:203], v[236:237], off offset:64
	s_waitcnt vmcnt(16)
	v_pk_fma_f32 v[168:169], v[168:169], s[16:17], v[98:99] op_sel_hi:[1,0,1]
	v_pk_fma_f32 v[170:171], v[170:171], s[16:17], v[100:101] op_sel_hi:[1,0,1]
	global_store_dwordx4 v[204:205], v[168:171], off offset:576 sc1
	s_nop 0
	global_load_dwordx4 v[168:171], v[240:241], off
	s_waitcnt vmcnt(16)
	v_pk_fma_f32 v[174:175], v[174:175], s[16:17], v[96:97] op_sel_hi:[1,0,1]
	v_pk_fma_f32 v[172:173], v[172:173], s[16:17], v[94:95] op_sel_hi:[1,0,1]
	global_store_dwordx4 v[208:209], v[172:175], off offset:512 sc1
	s_nop 0
	global_load_dwordx4 v[172:175], v[240:241], off offset:64
	s_waitcnt vmcnt(16)
	v_pk_fma_f32 v[178:179], v[178:179], s[16:17], v[92:93] op_sel_hi:[1,0,1]
	v_pk_fma_f32 v[176:177], v[176:177], s[16:17], v[90:91] op_sel_hi:[1,0,1]
	global_store_dwordx4 v[208:209], v[176:179], off offset:576 sc1
	s_nop 0
	global_load_dwordx4 v[176:179], v[244:245], off
	s_waitcnt vmcnt(16)
	v_pk_fma_f32 v[182:183], v[182:183], s[16:17], v[80:81] op_sel_hi:[1,0,1]
	v_pk_fma_f32 v[180:181], v[180:181], s[16:17], v[78:79] op_sel_hi:[1,0,1]
	global_store_dwordx4 v[226:227], v[180:183], off offset:512 sc1
	s_nop 0
	global_load_dwordx4 v[180:183], v[244:245], off offset:64
	s_waitcnt vmcnt(16)
	v_pk_fma_f32 v[186:187], v[186:187], s[16:17], v[68:69] op_sel_hi:[1,0,1]
	v_pk_fma_f32 v[184:185], v[184:185], s[16:17], v[66:67] op_sel_hi:[1,0,1]
	global_store_dwordx4 v[226:227], v[184:187], off offset:576 sc1
	s_nop 0
	global_load_dwordx4 v[184:187], v[248:249], off
	s_waitcnt vmcnt(16)
	v_pk_fma_f32 v[190:191], v[190:191], s[16:17], v[64:65] op_sel_hi:[1,0,1]
	v_pk_fma_f32 v[188:189], v[188:189], s[16:17], v[62:63] op_sel_hi:[1,0,1]
	global_store_dwordx4 v[230:231], v[188:191], off offset:512 sc1
	s_nop 0
	global_load_dwordx4 v[188:191], v[248:249], off offset:64
	s_waitcnt vmcnt(16)
	v_pk_fma_f32 v[194:195], v[194:195], s[16:17], v[60:61] op_sel_hi:[1,0,1]
	v_pk_fma_f32 v[192:193], v[192:193], s[16:17], v[58:59] op_sel_hi:[1,0,1]
	global_store_dwordx4 v[230:231], v[192:195], off offset:576 sc1
	s_nop 0
	global_load_dwordx4 v[192:195], v[236:237], off offset:512
	s_waitcnt vmcnt(16)
	v_pk_fma_f32 v[198:199], v[198:199], s[16:17], v[84:85] op_sel_hi:[1,0,1]
	v_pk_fma_f32 v[196:197], v[196:197], s[16:17], v[82:83] op_sel_hi:[1,0,1]
	global_store_dwordx4 v[234:235], v[196:199], off sc1
	s_nop 0
	global_load_dwordx4 v[196:199], v[236:237], off offset:576
	s_waitcnt vmcnt(16)
	v_pk_fma_f32 v[202:203], v[202:203], s[16:17], v[72:73] op_sel_hi:[1,0,1]
	v_pk_fma_f32 v[200:201], v[200:201], s[16:17], v[70:71] op_sel_hi:[1,0,1]
	global_store_dwordx4 v[234:235], v[200:203], off offset:64 sc1
	s_nop 0
	global_load_dwordx4 v[200:203], v[240:241], off offset:512
	s_waitcnt vmcnt(16)
	v_pk_fma_f32 v[170:171], v[170:171], s[16:17], v[56:57] op_sel_hi:[1,0,1]
	v_pk_fma_f32 v[168:169], v[168:169], s[16:17], v[54:55] op_sel_hi:[1,0,1]
	global_store_dwordx4 v[238:239], v[168:171], off sc1
	s_nop 0
	global_load_dwordx4 v[168:171], v[240:241], off offset:576
	s_waitcnt vmcnt(16)
	v_pk_fma_f32 v[174:175], v[174:175], s[16:17], v[52:53] op_sel_hi:[1,0,1]
	v_pk_fma_f32 v[172:173], v[172:173], s[16:17], v[50:51] op_sel_hi:[1,0,1]
	global_store_dwordx4 v[238:239], v[172:175], off offset:64 sc1
	s_nop 0
	global_load_dwordx4 v[172:175], v[244:245], off offset:512
	s_waitcnt vmcnt(16)
	v_pk_fma_f32 v[178:179], v[178:179], s[16:17], v[48:49] op_sel_hi:[1,0,1]
	v_pk_fma_f32 v[176:177], v[176:177], s[16:17], v[46:47] op_sel_hi:[1,0,1]
	global_store_dwordx4 v[242:243], v[176:179], off sc1
	s_nop 0
	global_load_dwordx4 v[176:179], v[244:245], off offset:576
	s_waitcnt vmcnt(16)
	v_pk_fma_f32 v[182:183], v[182:183], s[16:17], v[44:45] op_sel_hi:[1,0,1]
	v_pk_fma_f32 v[180:181], v[180:181], s[16:17], v[42:43] op_sel_hi:[1,0,1]
	global_store_dwordx4 v[242:243], v[180:183], off offset:64 sc1
	s_nop 0
	global_load_dwordx4 v[180:183], v[248:249], off offset:512
	s_waitcnt vmcnt(16)
	v_pk_fma_f32 v[186:187], v[186:187], s[16:17], v[40:41] op_sel_hi:[1,0,1]
	v_pk_fma_f32 v[184:185], v[184:185], s[16:17], v[38:39] op_sel_hi:[1,0,1]
	global_store_dwordx4 v[246:247], v[184:187], off sc1
	s_nop 0
	global_load_dwordx4 v[184:187], v[248:249], off offset:576
	s_waitcnt vmcnt(16)
	v_pk_fma_f32 v[190:191], v[190:191], s[16:17], v[32:33] op_sel_hi:[1,0,1]
	v_pk_fma_f32 v[188:189], v[188:189], s[16:17], v[30:31] op_sel_hi:[1,0,1]
	global_store_dwordx4 v[246:247], v[188:191], off offset:64 sc1
	s_waitcnt vmcnt(15)
	v_pk_fma_f32 v[194:195], v[194:195], s[16:17], v[36:37] op_sel_hi:[1,0,1]
	v_pk_fma_f32 v[192:193], v[192:193], s[16:17], v[34:35] op_sel_hi:[1,0,1]
	global_store_dwordx4 v[234:235], v[192:195], off offset:512 sc1
	s_waitcnt vmcnt(14)
	v_pk_fma_f32 v[198:199], v[198:199], s[16:17], v[28:29] op_sel_hi:[1,0,1]
	v_pk_fma_f32 v[196:197], v[196:197], s[16:17], v[26:27] op_sel_hi:[1,0,1]
	global_store_dwordx4 v[234:235], v[196:199], off offset:576 sc1
	s_waitcnt vmcnt(13)
	v_pk_fma_f32 v[202:203], v[202:203], s[16:17], v[24:25] op_sel_hi:[1,0,1]
	v_pk_fma_f32 v[200:201], v[200:201], s[16:17], v[22:23] op_sel_hi:[1,0,1]
	global_store_dwordx4 v[238:239], v[200:203], off offset:512 sc1
	s_waitcnt vmcnt(12)
	v_pk_fma_f32 v[170:171], v[170:171], s[16:17], v[20:21] op_sel_hi:[1,0,1]
	v_pk_fma_f32 v[168:169], v[168:169], s[16:17], v[18:19] op_sel_hi:[1,0,1]
	global_store_dwordx4 v[238:239], v[168:171], off offset:576 sc1
	s_waitcnt vmcnt(11)
	v_pk_fma_f32 v[174:175], v[174:175], s[16:17], v[16:17] op_sel_hi:[1,0,1]
	v_pk_fma_f32 v[172:173], v[172:173], s[16:17], v[14:15] op_sel_hi:[1,0,1]
	global_store_dwordx4 v[242:243], v[172:175], off offset:512 sc1
	s_waitcnt vmcnt(10)
	v_pk_fma_f32 v[178:179], v[178:179], s[16:17], v[12:13] op_sel_hi:[1,0,1]
	v_pk_fma_f32 v[176:177], v[176:177], s[16:17], v[10:11] op_sel_hi:[1,0,1]
	global_store_dwordx4 v[242:243], v[176:179], off offset:576 sc1
	s_waitcnt vmcnt(9)
	v_pk_fma_f32 v[182:183], v[182:183], s[16:17], v[8:9] op_sel_hi:[1,0,1]
	v_pk_fma_f32 v[180:181], v[180:181], s[16:17], v[6:7] op_sel_hi:[1,0,1]
	global_store_dwordx4 v[246:247], v[180:183], off offset:512 sc1
	s_waitcnt vmcnt(8)
	v_pk_fma_f32 v[186:187], v[186:187], s[16:17], v[4:5] op_sel_hi:[1,0,1]
	v_pk_fma_f32 v[184:185], v[184:185], s[16:17], v[2:3] op_sel_hi:[1,0,1]
	global_store_dwordx4 v[246:247], v[184:187], off offset:576 sc1

.LBB0_52:
	s_waitcnt vmcnt(0)
	v_cmp_eq_u32_e32 vcc, 0, v0
	s_waitcnt vmcnt(0) lgkmcnt(0)
	s_barrier
	s_and_saveexec_b64 s[16:17], vcc
	s_cbranch_execz .LBB0_35
	s_mov_b32 s100, s12
	s_ashr_i32 s13, s12, 31
	s_lshl_b64 s[12:13], s[12:13], 2
	s_add_u32 s12, s4, s12
	s_addc_u32 s13, s5, s13
	s_cmp_ge_u32 s100, 0x80
	s_cbranch_scc0 .Lnowb_12
	buffer_wbl2 sc1
.Lnowb_12:
	s_waitcnt vmcnt(0)
	v_mov_b64_e32 v[2:3], s[12:13]
	flat_atomic_add v[2:3], v213
	s_branch .LBB0_35

.LBB0_1602:
	s_or_b64 exec, exec, s[12:13]
	v_mov_b32_e32 v0, v211
	s_lshl_b32 s9, s9, 8
	v_ashrrev_i32_e32 v130, 2, v0
	v_and_b32_e32 v130, 0xffffffc0, v130
	v_and_or_b32 v131, v0, 15, s35
	v_add_u32_e32 v150, v131, v130
	v_lshrrev_b32_e32 v130, 1, v0
	v_lshrrev_b32_e32 v131, 2, v0
	v_and_b32_e32 v130, 0x60, v130
	v_and_b32_e32 v131, 12, v131
	v_or3_b32 v152, v130, v131, s9
	v_or_b32_e32 v142, 48, v150
	v_or_b32_e32 v148, 16, v150
	v_or_b32_e32 v144, 32, v150
	v_add_u32_e32 v140, 0x80, v150
	v_add_u32_e32 v134, 0xb0, v150
	v_add_u32_e32 v138, 0x90, v150
	v_add_u32_e32 v136, 0xa0, v150
	s_mov_b64 s[12:13], -1
	s_andn2_b64 vcc, exec, s[10:11]
	v_ashrrev_i32_e32 v153, 31, v152
	v_ashrrev_i32_e32 v151, 31, v150
	v_ashrrev_i32_e32 v143, 31, v142
	v_ashrrev_i32_e32 v149, 31, v148
	v_ashrrev_i32_e32 v145, 31, v144
	v_ashrrev_i32_e32 v135, 31, v134
	v_ashrrev_i32_e32 v141, 31, v140
	v_ashrrev_i32_e32 v139, 31, v138
	v_ashrrev_i32_e32 v137, 31, v136
	s_cbranch_vccnz .LBB0_1604
	v_lshlrev_b64 v[204:205], 12, v[142:143]
	v_lshl_add_u64 v[206:207], s[4:5], 0, v[204:205]
	v_lshlrev_b64 v[208:209], 12, v[150:151]
	v_lshl_add_u64 v[222:223], s[4:5], 0, v[208:209]
	v_lshlrev_b64 v[226:227], 2, v[152:153]
	v_lshl_add_u64 v[222:223], v[222:223], 0, v[226:227]
	s_mov_b32 s10, 0x3fb504f3
	s_mov_b64 s[12:13], 0
	v_lshlrev_b64 v[228:229], 12, v[148:149]
	v_lshl_add_u64 v[228:229], s[4:5], 0, v[228:229]
	v_lshl_add_u64 v[228:229], v[228:229], 0, v[226:227]
	v_lshlrev_b64 v[230:231], 12, v[144:145]
	v_lshl_add_u64 v[230:231], s[4:5], 0, v[230:231]
	v_lshl_add_u64 v[230:231], v[230:231], 0, v[226:227]
	v_lshl_add_u64 v[232:233], v[206:207], 0, v[226:227]
	v_lshlrev_b64 v[234:235], 12, v[134:135]
	v_lshl_add_u64 v[236:237], s[4:5], 0, v[234:235]
	v_lshlrev_b64 v[238:239], 12, v[140:141]
	v_lshl_add_u64 v[238:239], s[4:5], 0, v[238:239]
	v_lshl_add_u64 v[240:241], v[238:239], 0, v[226:227]
	v_lshlrev_b64 v[242:243], 12, v[138:139]
	v_lshl_add_u64 v[242:243], s[4:5], 0, v[242:243]
	v_lshl_add_u64 v[242:243], v[242:243], 0, v[226:227]
	v_lshlrev_b64 v[244:245], 12, v[136:137]
	v_lshl_add_u64 v[244:245], s[4:5], 0, v[244:245]
	v_lshl_add_u64 v[246:247], v[244:245], 0, v[226:227]
	v_lshl_add_u64 v[248:249], v[236:237], 0, v[226:227]
	global_load_dwordx4 v[164:167], v[222:223], off
	global_load_dwordx4 v[168:171], v[222:223], off offset:64
	global_load_dwordx4 v[172:175], v[228:229], off
	global_load_dwordx4 v[176:179], v[228:229], off offset:64
	global_load_dwordx4 v[180:183], v[230:231], off
	global_load_dwordx4 v[184:187], v[230:231], off offset:64
	global_load_dwordx4 v[188:191], v[232:233], off
	global_load_dwordx4 v[192:195], v[232:233], off offset:64
	global_load_dwordx4 v[196:199], v[222:223], off offset:512
	global_load_dwordx4 v[200:203], v[222:223], off offset:576
	s_waitcnt vmcnt(9)
	v_pk_fma_f32 v[166:167], v[166:167], s[10:11], v[128:129] op_sel_hi:[1,0,1]
	v_pk_fma_f32 v[164:165], v[164:165], s[10:11], v[126:127] op_sel_hi:[1,0,1]
	global_store_dwordx4 v[222:223], v[164:167], off sc1
	s_nop 0
	global_load_dwordx4 v[164:167], v[228:229], off offset:512
	s_waitcnt vmcnt(10)
	v_pk_fma_f32 v[170:171], v[170:171], s[10:11], v[124:125] op_sel_hi:[1,0,1]
	v_pk_fma_f32 v[168:169], v[168:169], s[10:11], v[122:123] op_sel_hi:[1,0,1]
	global_store_dwordx4 v[222:223], v[168:171], off offset:64 sc1
	s_nop 0
	global_load_dwordx4 v[168:171], v[228:229], off offset:576
	s_waitcnt vmcnt(11)
	v_pk_fma_f32 v[174:175], v[174:175], s[10:11], v[120:121] op_sel_hi:[1,0,1]
	v_pk_fma_f32 v[172:173], v[172:173], s[10:11], v[118:119] op_sel_hi:[1,0,1]
	global_store_dwordx4 v[228:229], v[172:175], off sc1
	s_nop 0
	global_load_dwordx4 v[172:175], v[230:231], off offset:512
	s_waitcnt vmcnt(12)
	v_pk_fma_f32 v[178:179], v[178:179], s[10:11], v[116:117] op_sel_hi:[1,0,1]
	v_pk_fma_f32 v[176:177], v[176:177], s[10:11], v[114:115] op_sel_hi:[1,0,1]
	global_store_dwordx4 v[228:229], v[176:179], off offset:64 sc1
	s_nop 0
	global_load_dwordx4 v[176:179], v[230:231], off offset:576
	s_waitcnt vmcnt(13)
	v_pk_fma_f32 v[182:183], v[182:183], s[10:11], v[112:113] op_sel_hi:[1,0,1]
	v_pk_fma_f32 v[180:181], v[180:181], s[10:11], v[110:111] op_sel_hi:[1,0,1]
	global_store_dwordx4 v[230:231], v[180:183], off sc1
	s_nop 0
	global_load_dwordx4 v[180:183], v[232:233], off offset:512
	s_waitcnt vmcnt(14)
	v_pk_fma_f32 v[186:187], v[186:187], s[10:11], v[108:109] op_sel_hi:[1,0,1]
	v_pk_fma_f32 v[184:185], v[184:185], s[10:11], v[106:107] op_sel_hi:[1,0,1]
	global_store_dwordx4 v[230:231], v[184:187], off offset:64 sc1
	s_nop 0
	global_load_dwordx4 v[184:187], v[232:233], off offset:576
	s_waitcnt vmcnt(15)
	v_pk_fma_f32 v[190:191], v[190:191], s[10:11], v[88:89] op_sel_hi:[1,0,1]
	v_pk_fma_f32 v[188:189], v[188:189], s[10:11], v[86:87] op_sel_hi:[1,0,1]
	global_store_dwordx4 v[232:233], v[188:191], off sc1
	s_nop 0
	global_load_dwordx4 v[188:191], v[240:241], off
	s_waitcnt vmcnt(16)
	v_pk_fma_f32 v[194:195], v[194:195], s[10:11], v[76:77] op_sel_hi:[1,0,1]
	v_pk_fma_f32 v[192:193], v[192:193], s[10:11], v[74:75] op_sel_hi:[1,0,1]
	global_store_dwordx4 v[232:233], v[192:195], off offset:64 sc1
	s_nop 0
	global_load_dwordx4 v[192:195], v[240:241], off offset:64
	s_waitcnt vmcnt(17)
	v_pk_fma_f32 v[198:199], v[198:199], s[10:11], v[104:105] op_sel_hi:[1,0,1]
	v_pk_fma_f32 v[196:197], v[196:197], s[10:11], v[102:103] op_sel_hi:[1,0,1]
	global_store_dwordx4 v[222:223], v[196:199], off offset:512 sc1
	s_nop 0
	global_load_dwordx4 v[196:199], v[242:243], off
	s_waitcnt vmcnt(18)
	v_pk_fma_f32 v[202:203], v[202:203], s[10:11], v[100:101] op_sel_hi:[1,0,1]
	v_pk_fma_f32 v[200:201], v[200:201], s[10:11], v[98:99] op_sel_hi:[1,0,1]
	global_store_dwordx4 v[222:223], v[200:203], off offset:576 sc1
	s_nop 0
	global_load_dwordx4 v[200:203], v[242:243], off offset:64
	s_waitcnt vmcnt(18)
	v_pk_fma_f32 v[166:167], v[166:167], s[10:11], v[96:97] op_sel_hi:[1,0,1]
	v_pk_fma_f32 v[164:165], v[164:165], s[10:11], v[94:95] op_sel_hi:[1,0,1]
	global_store_dwordx4 v[228:229], v[164:167], off offset:512 sc1
	s_nop 0
	global_load_dwordx4 v[164:167], v[246:247], off
	s_waitcnt vmcnt(18)
	v_pk_fma_f32 v[170:171], v[170:171], s[10:11], v[92:93] op_sel_hi:[1,0,1]
	v_pk_fma_f32 v[168:169], v[168:169], s[10:11], v[90:91] op_sel_hi:[1,0,1]
	global_store_dwordx4 v[228:229], v[168:171], off offset:576 sc1
	s_nop 0
	global_load_dwordx4 v[168:171], v[246:247], off offset:64
	s_waitcnt vmcnt(18)
	v_pk_fma_f32 v[174:175], v[174:175], s[10:11], v[80:81] op_sel_hi:[1,0,1]
	v_pk_fma_f32 v[172:173], v[172:173], s[10:11], v[78:79] op_sel_hi:[1,0,1]
	global_store_dwordx4 v[230:231], v[172:175], off offset:512 sc1
	s_nop 0
	global_load_dwordx4 v[172:175], v[248:249], off
	s_waitcnt vmcnt(18)
	v_pk_fma_f32 v[178:179], v[178:179], s[10:11], v[68:69] op_sel_hi:[1,0,1]
	v_pk_fma_f32 v[176:177], v[176:177], s[10:11], v[66:67] op_sel_hi:[1,0,1]
	global_store_dwordx4 v[230:231], v[176:179], off offset:576 sc1
	s_nop 0
	global_load_dwordx4 v[176:179], v[248:249], off offset:64
	s_waitcnt vmcnt(18)
	v_pk_fma_f32 v[182:183], v[182:183], s[10:11], v[64:65] op_sel_hi:[1,0,1]
	v_pk_fma_f32 v[180:181], v[180:181], s[10:11], v[62:63] op_sel_hi:[1,0,1]
	global_store_dwordx4 v[232:233], v[180:183], off offset:512 sc1
	s_nop 0
	global_load_dwordx4 v[180:183], v[240:241], off offset:512
	s_waitcnt vmcnt(18)
	v_pk_fma_f32 v[186:187], v[186:187], s[10:11], v[60:61] op_sel_hi:[1,0,1]
	v_pk_fma_f32 v[184:185], v[184:185], s[10:11], v[58:59] op_sel_hi:[1,0,1]
	global_store_dwordx4 v[232:233], v[184:187], off offset:576 sc1
	s_nop 0
	global_load_dwordx4 v[184:187], v[240:241], off offset:576
	s_waitcnt vmcnt(18)
	v_pk_fma_f32 v[190:191], v[190:191], s[10:11], v[84:85] op_sel_hi:[1,0,1]
	v_pk_fma_f32 v[188:189], v[188:189], s[10:11], v[82:83] op_sel_hi:[1,0,1]
	global_store_dwordx4 v[240:241], v[188:191], off sc1
	s_nop 0
	global_load_dwordx4 v[188:191], v[242:243], off offset:512
	s_waitcnt vmcnt(18)
	v_pk_fma_f32 v[194:195], v[194:195], s[10:11], v[72:73] op_sel_hi:[1,0,1]
	v_pk_fma_f32 v[192:193], v[192:193], s[10:11], v[70:71] op_sel_hi:[1,0,1]
	global_store_dwordx4 v[240:241], v[192:195], off offset:64 sc1
	s_nop 0
	global_load_dwordx4 v[192:195], v[242:243], off offset:576
	s_waitcnt vmcnt(18)
	v_pk_fma_f32 v[198:199], v[198:199], s[10:11], v[56:57] op_sel_hi:[1,0,1]
	v_pk_fma_f32 v[196:197], v[196:197], s[10:11], v[54:55] op_sel_hi:[1,0,1]
	global_store_dwordx4 v[242:243], v[196:199], off sc1
	s_nop 0
	global_load_dwordx4 v[196:199], v[246:247], off offset:512
	s_waitcnt vmcnt(18)
	v_pk_fma_f32 v[202:203], v[202:203], s[10:11], v[52:53] op_sel_hi:[1,0,1]
	v_pk_fma_f32 v[200:201], v[200:201], s[10:11], v[50:51] op_sel_hi:[1,0,1]
	global_store_dwordx4 v[242:243], v[200:203], off offset:64 sc1
	s_nop 0
	global_load_dwordx4 v[200:203], v[246:247], off offset:576
	s_waitcnt vmcnt(18)
	v_pk_fma_f32 v[166:167], v[166:167], s[10:11], v[48:49] op_sel_hi:[1,0,1]
	v_pk_fma_f32 v[164:165], v[164:165], s[10:11], v[46:47] op_sel_hi:[1,0,1]
	global_store_dwordx4 v[246:247], v[164:167], off sc1
	s_nop 0
	global_load_dwordx4 v[164:167], v[248:249], off offset:512
	s_waitcnt vmcnt(18)
	v_pk_fma_f32 v[170:171], v[170:171], s[10:11], v[44:45] op_sel_hi:[1,0,1]
	v_pk_fma_f32 v[168:169], v[168:169], s[10:11], v[42:43] op_sel_hi:[1,0,1]
	global_store_dwordx4 v[246:247], v[168:171], off offset:64 sc1
	s_nop 0
	global_load_dwordx4 v[168:171], v[248:249], off offset:576
	s_waitcnt vmcnt(18)
	v_pk_fma_f32 v[174:175], v[174:175], s[10:11], v[40:41] op_sel_hi:[1,0,1]
	v_pk_fma_f32 v[172:173], v[172:173], s[10:11], v[38:39] op_sel_hi:[1,0,1]
	global_store_dwordx4 v[248:249], v[172:175], off sc1
	s_waitcnt vmcnt(17)
	v_pk_fma_f32 v[178:179], v[178:179], s[10:11], v[32:33] op_sel_hi:[1,0,1]
	v_pk_fma_f32 v[176:177], v[176:177], s[10:11], v[30:31] op_sel_hi:[1,0,1]
	global_store_dwordx4 v[248:249], v[176:179], off offset:64 sc1
	s_waitcnt vmcnt(16)
	v_pk_fma_f32 v[182:183], v[182:183], s[10:11], v[36:37] op_sel_hi:[1,0,1]
	v_pk_fma_f32 v[180:181], v[180:181], s[10:11], v[34:35] op_sel_hi:[1,0,1]
	global_store_dwordx4 v[240:241], v[180:183], off offset:512 sc1
	s_waitcnt vmcnt(15)
	v_pk_fma_f32 v[186:187], v[186:187], s[10:11], v[28:29] op_sel_hi:[1,0,1]
	v_pk_fma_f32 v[184:185], v[184:185], s[10:11], v[26:27] op_sel_hi:[1,0,1]
	global_store_dwordx4 v[240:241], v[184:187], off offset:576 sc1
	s_waitcnt vmcnt(14)
	v_pk_fma_f32 v[190:191], v[190:191], s[10:11], v[24:25] op_sel_hi:[1,0,1]
	v_pk_fma_f32 v[188:189], v[188:189], s[10:11], v[22:23] op_sel_hi:[1,0,1]
	global_store_dwordx4 v[242:243], v[188:191], off offset:512 sc1
	s_waitcnt vmcnt(13)
	v_pk_fma_f32 v[194:195], v[194:195], s[10:11], v[20:21] op_sel_hi:[1,0,1]
	v_pk_fma_f32 v[192:193], v[192:193], s[10:11], v[18:19] op_sel_hi:[1,0,1]
	global_store_dwordx4 v[242:243], v[192:195], off offset:576 sc1
	s_waitcnt vmcnt(12)
	v_pk_fma_f32 v[198:199], v[198:199], s[10:11], v[16:17] op_sel_hi:[1,0,1]
	v_pk_fma_f32 v[196:197], v[196:197], s[10:11], v[14:15] op_sel_hi:[1,0,1]
	global_store_dwordx4 v[246:247], v[196:199], off offset:512 sc1
	s_waitcnt vmcnt(11)
	v_pk_fma_f32 v[202:203], v[202:203], s[10:11], v[12:13] op_sel_hi:[1,0,1]
	v_pk_fma_f32 v[200:201], v[200:201], s[10:11], v[10:11] op_sel_hi:[1,0,1]
	global_store_dwordx4 v[246:247], v[200:203], off offset:576 sc1
	s_waitcnt vmcnt(10)
	v_pk_fma_f32 v[166:167], v[166:167], s[10:11], v[8:9] op_sel_hi:[1,0,1]
	v_pk_fma_f32 v[164:165], v[164:165], s[10:11], v[6:7] op_sel_hi:[1,0,1]
	global_store_dwordx4 v[248:249], v[164:167], off offset:512 sc1
	s_waitcnt vmcnt(9)
	v_pk_fma_f32 v[170:171], v[170:171], s[10:11], v[4:5] op_sel_hi:[1,0,1]
	v_pk_fma_f32 v[168:169], v[168:169], s[10:11], v[2:3] op_sel_hi:[1,0,1]
	global_store_dwordx4 v[248:249], v[168:171], off offset:576 sc1

.LBB0_1606:
	s_waitcnt vmcnt(0)
	v_cmp_eq_u32_e32 vcc, 0, v0
	s_waitcnt vmcnt(0) lgkmcnt(0)
	s_barrier
	s_and_saveexec_b64 s[10:11], vcc
	s_cbranch_execz .LBB0_1589
	s_mov_b32 s100, s8
	s_ashr_i32 s9, s8, 31
	s_lshl_b64 s[8:9], s[8:9], 2
	s_add_u32 s8, s2, s8
	s_addc_u32 s9, s3, s9
	s_cmp_ge_u32 s100, 0x80
	s_cbranch_scc0 .Lnowb_8
	buffer_wbl2 sc1
.Lnowb_8:
	s_waitcnt vmcnt(0)
	v_mov_b64_e32 v[2:3], s[8:9]
	flat_atomic_add v[2:3], v213
	s_branch .LBB0_1589
